# deferred transposes staggered: blocks >=256 transpose before attention L0, blocks <256 after
# speedup vs baseline: 1.0026x; 1.0026x over previous
.LBB0_354:
	s_or_b64 exec, exec, s[6:7]
	s_cmpk_lt_i32 s69, 0x400
	s_cselect_b64 s[0:1], -1, 0
	v_writelane_b32 v253, s0, 16
	s_cmpk_gt_i32 s69, 0x3ff
	v_lshlrev_b32_e32 v158, 4, v233
	v_writelane_b32 v253, s1, 17
	v_cmp_eq_u32_e32 vcc, 0, v233
	s_waitcnt lgkmcnt(0)
	s_barrier
	v_writelane_b32 v253, s69, 18
	s_cmpk_lt_u32 s69, 0x100
	s_cbranch_scc1 .Ltre_done
	v_readlane_b32 s2, v253, 0
	v_readlane_b32 s3, v253, 1
	s_load_dwordx2 s[4:5], s[2:3], 0x160
	s_load_dwordx2 s[6:7], s[2:3], 0x168
	v_lshrrev_b32_e32 v60, 4, v146
	v_and_b32_e32 v60, 15, v60
	v_and_b32_e32 v61, 15, v146
	v_lshlrev_b32_e32 v61, 2, v61
	v_lshrrev_b32_e32 v62, 3, v146
	v_and_b32_e32 v62, 31, v62
	v_and_b32_e32 v63, 7, v146
	v_mul_u32_u24_e32 v64, 65, v60
	v_add_u32_e32 v64, v64, v61
	v_lshlrev_b32_e32 v64, 2, v64
	v_mul_u32_u24_e32 v65, 0x208, v63
	v_add_u32_e32 v65, v65, v62
	v_lshlrev_b32_e32 v65, 2, v65
	s_mov_b32 s1, s69
	s_waitcnt lgkmcnt(0)
	s_cmp_lt_u32 s1, 0x6d0
	s_cbranch_scc0 .Ltre_done

.Ltre_dd:
	s_load_dwordx2 s[16:17], s[2:3], s12
	s_lshl_b32 s14, s14, 7
	s_lshl_b32 s18, s15, 6
	v_add_u32_e32 v0, s18, v60
	v_mul_lo_u32 v0, v0, s10
	v_add_u32_e32 v1, s14, v61
	v_cmp_gt_u32_e64 s[24:25], s10, v1
	v_add_u32_e32 v2, 64, v1
	v_cmp_gt_u32_e64 s[26:27], s10, v2
	v_add_u32_e32 v2, v0, v1
	v_lshlrev_b32_e32 v2, 2, v2
	v_add_u32_e32 v3, 0x100, v2
	s_lshl_b32 s19, s10, 6
	v_mov_b32_e32 v8, 0
	v_mov_b32_e32 v9, 0
	v_mov_b32_e32 v10, 0
	v_mov_b32_e32 v11, 0
	v_mov_b32_e32 v12, 0
	v_mov_b32_e32 v13, 0
	v_mov_b32_e32 v14, 0
	v_mov_b32_e32 v15, 0
	v_mov_b32_e32 v16, 0
	v_mov_b32_e32 v17, 0
	v_mov_b32_e32 v18, 0
	v_mov_b32_e32 v19, 0
	v_mov_b32_e32 v20, 0
	v_mov_b32_e32 v21, 0
	v_mov_b32_e32 v22, 0
	v_mov_b32_e32 v23, 0
	v_mov_b32_e32 v24, 0
	v_mov_b32_e32 v25, 0
	v_mov_b32_e32 v26, 0
	v_mov_b32_e32 v27, 0
	v_mov_b32_e32 v28, 0
	v_mov_b32_e32 v29, 0
	v_mov_b32_e32 v30, 0
	v_mov_b32_e32 v31, 0
	v_mov_b32_e32 v32, 0
	v_mov_b32_e32 v33, 0
	v_mov_b32_e32 v34, 0
	v_mov_b32_e32 v35, 0
	v_mov_b32_e32 v36, 0
	v_mov_b32_e32 v37, 0
	v_mov_b32_e32 v38, 0
	v_mov_b32_e32 v39, 0
	s_waitcnt lgkmcnt(0)
	s_mov_b64 exec, s[24:25]
	global_load_dwordx4 v[8:11], v2, s[16:17] nt
	v_add_u32_e32 v2, s19, v2
	global_load_dwordx4 v[12:15], v2, s[16:17] nt
	v_add_u32_e32 v2, s19, v2
	global_load_dwordx4 v[16:19], v2, s[16:17] nt
	v_add_u32_e32 v2, s19, v2
	global_load_dwordx4 v[20:23], v2, s[16:17] nt
	s_mov_b64 exec, s[26:27]
	global_load_dwordx4 v[24:27], v3, s[16:17] nt
	v_add_u32_e32 v3, s19, v3
	global_load_dwordx4 v[28:31], v3, s[16:17] nt
	v_add_u32_e32 v3, s19, v3
	global_load_dwordx4 v[32:35], v3, s[16:17] nt
	v_add_u32_e32 v3, s19, v3
	global_load_dwordx4 v[36:39], v3, s[16:17] nt
	s_mov_b64 exec, -1
	v_add_u32_e32 v4, s14, v62
	v_lshlrev_b32_e32 v4, 11, v4
	v_lshl_add_u32 v4, v63, 4, v4
	s_lshl_b32 s18, s15, 7
	s_add_u32 s18, s18, s13
	v_add_u32_e32 v4, s18, v4
	v_add_u32_e32 v5, 0x10000, v4
	v_add_u32_e32 v6, 0x20000, v4
	v_add_u32_e32 v7, 0x30000, v4
	s_barrier
	s_waitcnt vmcnt(0)
	ds_write_b32 v64, v8
	ds_write_b32 v64, v9 offset:4
	ds_write_b32 v64, v10 offset:8
	ds_write_b32 v64, v11 offset:12
	ds_write_b32 v64, v12 offset:4160
	ds_write_b32 v64, v13 offset:4164
	ds_write_b32 v64, v14 offset:4168
	ds_write_b32 v64, v15 offset:4172
	ds_write_b32 v64, v16 offset:8320
	ds_write_b32 v64, v17 offset:8324
	ds_write_b32 v64, v18 offset:8328
	ds_write_b32 v64, v19 offset:8332
	ds_write_b32 v64, v20 offset:12480
	ds_write_b32 v64, v21 offset:12484
	ds_write_b32 v64, v22 offset:12488
	ds_write_b32 v64, v23 offset:12492
	ds_write_b32 v64, v24 offset:16640
	ds_write_b32 v64, v25 offset:16644
	ds_write_b32 v64, v26 offset:16648
	ds_write_b32 v64, v27 offset:16652
	ds_write_b32 v64, v28 offset:20800
	ds_write_b32 v64, v29 offset:20804
	ds_write_b32 v64, v30 offset:20808
	ds_write_b32 v64, v31 offset:20812
	ds_write_b32 v64, v32 offset:24960
	ds_write_b32 v64, v33 offset:24964
	ds_write_b32 v64, v34 offset:24968
	ds_write_b32 v64, v35 offset:24972
	ds_write_b32 v64, v36 offset:29120
	ds_write_b32 v64, v37 offset:29124
	ds_write_b32 v64, v38 offset:29128
	ds_write_b32 v64, v39 offset:29132
	s_waitcnt lgkmcnt(0)
	s_barrier
	ds_read_b32 v40, v65
	ds_read_b32 v41, v65 offset:260
	ds_read_b32 v42, v65 offset:520
	ds_read_b32 v43, v65 offset:780
	ds_read_b32 v44, v65 offset:1040
	ds_read_b32 v45, v65 offset:1300
	ds_read_b32 v46, v65 offset:1560
	ds_read_b32 v47, v65 offset:1820
	s_waitcnt lgkmcnt(0)
	v_cvt_pk_bf16_f32 v48, v40, v41
	v_cvt_pk_bf16_f32 v49, v42, v43
	v_cvt_pk_bf16_f32 v50, v44, v45
	v_cvt_pk_bf16_f32 v51, v46, v47
	global_store_dwordx4 v4, v[48:51], s[4:5]
	s_nop 1
	ds_read_b32 v40, v65 offset:128
	ds_read_b32 v41, v65 offset:388
	ds_read_b32 v42, v65 offset:648
	ds_read_b32 v43, v65 offset:908
	ds_read_b32 v44, v65 offset:1168
	ds_read_b32 v45, v65 offset:1428
	ds_read_b32 v46, v65 offset:1688
	ds_read_b32 v47, v65 offset:1948
	s_waitcnt lgkmcnt(0)
	v_cvt_pk_bf16_f32 v48, v40, v41
	v_cvt_pk_bf16_f32 v49, v42, v43
	v_cvt_pk_bf16_f32 v50, v44, v45
	v_cvt_pk_bf16_f32 v51, v46, v47
	global_store_dwordx4 v5, v[48:51], s[4:5]
	s_nop 1
	ds_read_b32 v40, v65 offset:16640
	ds_read_b32 v41, v65 offset:16900
	ds_read_b32 v42, v65 offset:17160
	ds_read_b32 v43, v65 offset:17420
	ds_read_b32 v44, v65 offset:17680
	ds_read_b32 v45, v65 offset:17940
	ds_read_b32 v46, v65 offset:18200
	ds_read_b32 v47, v65 offset:18460
	s_waitcnt lgkmcnt(0)
	v_cvt_pk_bf16_f32 v48, v40, v41
	v_cvt_pk_bf16_f32 v49, v42, v43
	v_cvt_pk_bf16_f32 v50, v44, v45
	v_cvt_pk_bf16_f32 v51, v46, v47
	global_store_dwordx4 v6, v[48:51], s[4:5]
	s_nop 1
	ds_read_b32 v40, v65 offset:16768
	ds_read_b32 v41, v65 offset:17028
	ds_read_b32 v42, v65 offset:17288
	ds_read_b32 v43, v65 offset:17548
	ds_read_b32 v44, v65 offset:17808
	ds_read_b32 v45, v65 offset:18068
	ds_read_b32 v46, v65 offset:18328
	ds_read_b32 v47, v65 offset:18588
	s_waitcnt lgkmcnt(0)
	v_cvt_pk_bf16_f32 v48, v40, v41
	v_cvt_pk_bf16_f32 v49, v42, v43
	v_cvt_pk_bf16_f32 v50, v44, v45
	v_cvt_pk_bf16_f32 v51, v46, v47
	global_store_dwordx4 v7, v[48:51], s[4:5]
	s_nop 1
	s_add_u32 s1, s1, s6
	s_cmp_lt_u32 s1, 0x6d0
	s_cbranch_scc1 .Ltre_task
	s_barrier
.Ltre_done:
	s_cmpk_gt_i32 s69, 0x3ff
	s_cbranch_scc1 .LBB0_407
	v_readlane_b32 s0, v253, 0
	v_readlane_b32 s1, v253, 1
	s_load_dwordx2 s[0:1], s[0:1], 0x160
	v_mov_b32_e32 v164, 0
	v_and_b32_e32 v0, 56, v152
	v_mov_b32_e32 v159, v164
	v_mul_u32_u24_e32 v1, 0x50, v149
	s_waitcnt lgkmcnt(0)
	s_add_u32 s82, s0, 0x3000000
	s_addc_u32 s83, s1, 0
	v_lshlrev_b32_e32 v2, 1, v0
	v_lshl_add_u64 v[166:167], s[82:83], 0, v[158:159]
	v_lshl_add_u32 v159, v1, 1, v2
	v_mbcnt_hi_u32_b32 v2, -1, v145
	s_add_u32 s3, s0, 0xb440000
	v_and_b32_e32 v4, 64, v2
	s_addc_u32 s70, s1, 0
	v_xor_b32_e32 v3, 16, v2
	v_add_u32_e32 v4, 64, v4
	s_add_u32 s84, s0, 0x2000000
	v_cndmask_b32_e64 v168, 0, 1.0, vcc
	v_cmp_lt_i32_e32 vcc, v3, v4
	s_addc_u32 s85, s1, 0
	s_add_u32 s2, s0, 0xf682100
	v_cndmask_b32_e32 v3, v2, v3, vcc
	v_lshlrev_b32_e32 v161, 2, v3
	v_xor_b32_e32 v3, 32, v2
	v_writelane_b32 v253, s2, 19
	s_addc_u32 s2, s1, 0
	v_cmp_lt_i32_e32 vcc, v3, v4
	s_add_u32 s0, s0, 0xf782100
	v_mul_u32_u24_e32 v1, 0xa0, v148
	v_cndmask_b32_e32 v2, v2, v3, vcc
	v_lshlrev_b32_e32 v174, 1, v0
	s_mov_b32 s81, 0
	v_writelane_b32 v253, s2, 21
	s_addc_u32 s78, s1, 0
	v_lshlrev_b32_e32 v170, 14, v149
	v_mov_b32_e32 v171, v164
	v_lshlrev_b32_e32 v172, 10, v149
	v_mov_b32_e32 v173, v164
	v_lshlrev_b32_e32 v163, 2, v2
	s_movk_i32 s79, 0x1400
	v_mov_b32_e32 v176, v174
	v_mov_b32_e32 v177, v164
	s_mov_b64 s[86:87], 0x80
	s_movk_i32 s76, 0xfeff
	s_mov_b32 s77, 0xf149f2ca
	s_movk_i32 s68, 0xfefe
	v_add_u32_e32 v169, v158, v1
	v_mov_b32_e32 v244, 0xf149f2ca
	v_writelane_b32 v253, s0, 22
	s_branch .LBB0_358

.LBB0_407:
	s_cmpk_gt_u32 s69, 0xff
	s_cbranch_scc1 .Ltr_done
	v_readlane_b32 s2, v253, 0
	v_readlane_b32 s3, v253, 1
	s_load_dwordx2 s[4:5], s[2:3], 0x160
	s_load_dwordx2 s[6:7], s[2:3], 0x168
	v_lshrrev_b32_e32 v60, 4, v146
	v_and_b32_e32 v60, 15, v60
	v_and_b32_e32 v61, 15, v146
	v_lshlrev_b32_e32 v61, 2, v61
	v_lshrrev_b32_e32 v62, 3, v146
	v_and_b32_e32 v62, 31, v62
	v_and_b32_e32 v63, 7, v146
	v_mul_u32_u24_e32 v64, 65, v60
	v_add_u32_e32 v64, v64, v61
	v_lshlrev_b32_e32 v64, 2, v64
	v_mul_u32_u24_e32 v65, 0x208, v63
	v_add_u32_e32 v65, v65, v62
	v_lshlrev_b32_e32 v65, 2, v65
	s_mov_b32 s1, s69
	s_waitcnt lgkmcnt(0)
	s_cmp_lt_u32 s1, 0x6d0
	s_cbranch_scc0 .Ltr_done
